# GEMM epilogues: SwiGLU with packed f32 ops and batched transcendentals; residual-add epilogues keep 12 residual loads in flight instead of one per wait; NSA branch epilogues likewise
# speedup vs baseline: 1.0070x; 1.0070x over previous
.LBB0_600:
	s_ashr_i32 s28, s59, 3
	v_lshl_or_b32 v140, s60, 8, v165
	s_mul_hi_i32 s29, s28, 0x9000
	s_mul_i32 s28, s28, 0x9000
	s_add_u32 s28, s50, s28
	v_ashrrev_i32_e32 v141, 31, v140
	s_addc_u32 s29, s51, s29
	v_lshlrev_b64 v[152:153], 2, v[140:141]
	v_lshl_add_u64 v[160:161], s[28:29], 0, v[152:153]
	global_load_dwordx4 v[140:143], v[160:161], off offset:16
	global_load_dwordx4 v[144:147], v[160:161], off
	v_lshl_add_u32 v162, s59, 8, v159
	v_ashrrev_i32_e32 v163, 31, v162
	s_mov_b64 s[28:29], 0x80000
	s_and_b64 vcc, exec, s[4:5]
	s_waitcnt vmcnt(0)
	v_pk_mul_f32 v[150:151], v[142:143], 0.5 op_sel_hi:[1,0]
	v_pk_mul_f32 v[154:155], v[146:147], 0.5 op_sel_hi:[1,0]
	v_pk_mul_f32 v[156:157], v[144:145], 0.5 op_sel_hi:[1,0]
	v_pk_mul_f32 v[148:149], v[140:141], 0.5 op_sel_hi:[1,0]
	global_load_dwordx4 v[140:143], v[160:161], off offset:528
	global_load_dwordx4 v[144:147], v[160:161], off offset:512
	v_mov_b32_e32 v160, v162
	v_ashrrev_i32_e32 v161, 31, v160
	v_lshlrev_b64 v[160:161], 12, v[160:161]
	v_lshl_add_u64 v[170:171], s[2:3], 0, v[160:161]
	v_lshl_add_u64 v[170:171], v[170:171], 0, v[152:153]
	global_load_dwordx4 v[176:179], v[170:171], off
	global_load_dwordx4 v[180:183], v[170:171], off offset:16
	global_load_dwordx4 v[184:187], v[170:171], off offset:512
	global_load_dwordx4 v[188:191], v[170:171], off offset:528
	v_add_u32_e32 v160, 16, v162
	v_ashrrev_i32_e32 v161, 31, v160
	v_lshlrev_b64 v[160:161], 12, v[160:161]
	v_lshl_add_u64 v[172:173], s[2:3], 0, v[160:161]
	v_lshl_add_u64 v[172:173], v[172:173], 0, v[152:153]
	global_load_dwordx4 v[192:195], v[172:173], off
	global_load_dwordx4 v[214:217], v[172:173], off offset:16
	global_load_dwordx4 v[218:221], v[172:173], off offset:512
	global_load_dwordx4 v[222:225], v[172:173], off offset:528
	v_add_u32_e32 v160, 32, v162
	v_ashrrev_i32_e32 v161, 31, v160
	v_lshlrev_b64 v[160:161], 12, v[160:161]
	v_lshl_add_u64 v[174:175], s[2:3], 0, v[160:161]
	v_lshl_add_u64 v[174:175], v[174:175], 0, v[152:153]
	global_load_dwordx4 v[226:229], v[174:175], off
	global_load_dwordx4 v[230:233], v[174:175], off offset:16
	global_load_dwordx4 v[234:237], v[174:175], off offset:512
	global_load_dwordx4 v[238:241], v[174:175], off offset:528
	s_waitcnt vmcnt(12)
	v_pk_mul_f32 v[142:143], v[142:143], 0.5 op_sel_hi:[1,0]
	v_pk_mul_f32 v[146:147], v[146:147], 0.5 op_sel_hi:[1,0]
	v_pk_mul_f32 v[144:145], v[144:145], 0.5 op_sel_hi:[1,0]
	v_pk_mul_f32 v[140:141], v[140:141], 0.5 op_sel_hi:[1,0]
	v_mov_b32_e32 v160, v162
	v_ashrrev_i32_e32 v161, 31, v160
	v_lshlrev_b64 v[160:161], 12, v[160:161]
	v_lshl_add_u64 v[168:169], s[20:21], 0, v[160:161]
	v_lshl_add_u64 v[168:169], v[168:169], 0, v[152:153]
	s_waitcnt vmcnt(11)
	v_pk_fma_f32 v[126:127], v[126:127], v[156:157], v[176:177]
	v_pk_fma_f32 v[128:129], v[128:129], v[154:155], v[178:179]
	global_store_dwordx4 v[168:169], v[126:129], off
	s_waitcnt vmcnt(11)
	v_pk_fma_f32 v[122:123], v[122:123], v[148:149], v[180:181]
	v_pk_fma_f32 v[124:125], v[124:125], v[150:151], v[182:183]
	global_store_dwordx4 v[168:169], v[122:125], off offset:16
	s_waitcnt vmcnt(11)
	v_pk_fma_f32 v[118:119], v[118:119], v[144:145], v[184:185]
	v_pk_fma_f32 v[120:121], v[120:121], v[146:147], v[186:187]
	global_store_dwordx4 v[168:169], v[118:121], off offset:512
	s_waitcnt vmcnt(11)
	v_pk_fma_f32 v[114:115], v[114:115], v[140:141], v[188:189]
	v_pk_fma_f32 v[116:117], v[116:117], v[142:143], v[190:191]
	global_store_dwordx4 v[168:169], v[114:117], off offset:528
	v_add_u32_e32 v160, 48, v162
	v_ashrrev_i32_e32 v161, 31, v160
	v_lshlrev_b64 v[160:161], 12, v[160:161]
	v_lshl_add_u64 v[170:171], s[2:3], 0, v[160:161]
	v_lshl_add_u64 v[170:171], v[170:171], 0, v[152:153]
	global_load_dwordx4 v[176:179], v[170:171], off
	global_load_dwordx4 v[180:183], v[170:171], off offset:16
	global_load_dwordx4 v[184:187], v[170:171], off offset:512
	global_load_dwordx4 v[188:191], v[170:171], off offset:528
	v_add_u32_e32 v160, 16, v162
	v_ashrrev_i32_e32 v161, 31, v160
	v_lshlrev_b64 v[160:161], 12, v[160:161]
	v_lshl_add_u64 v[168:169], s[20:21], 0, v[160:161]
	v_lshl_add_u64 v[168:169], v[168:169], 0, v[152:153]
	s_waitcnt vmcnt(15)
	v_pk_fma_f32 v[110:111], v[110:111], v[156:157], v[192:193]
	v_pk_fma_f32 v[112:113], v[112:113], v[154:155], v[194:195]
	global_store_dwordx4 v[168:169], v[110:113], off
	s_waitcnt vmcnt(15)
	v_pk_fma_f32 v[106:107], v[106:107], v[148:149], v[214:215]
	v_pk_fma_f32 v[108:109], v[108:109], v[150:151], v[216:217]
	global_store_dwordx4 v[168:169], v[106:109], off offset:16
	s_waitcnt vmcnt(15)
	v_pk_fma_f32 v[102:103], v[102:103], v[144:145], v[218:219]
	v_pk_fma_f32 v[104:105], v[104:105], v[146:147], v[220:221]
	global_store_dwordx4 v[168:169], v[102:105], off offset:512
	s_waitcnt vmcnt(15)
	v_pk_fma_f32 v[98:99], v[98:99], v[140:141], v[222:223]
	v_pk_fma_f32 v[100:101], v[100:101], v[142:143], v[224:225]
	global_store_dwordx4 v[168:169], v[98:101], off offset:528
	v_add_u32_e32 v160, 128, v162
	v_ashrrev_i32_e32 v161, 31, v160
	v_lshlrev_b64 v[160:161], 12, v[160:161]
	v_lshl_add_u64 v[172:173], s[2:3], 0, v[160:161]
	v_lshl_add_u64 v[172:173], v[172:173], 0, v[152:153]
	global_load_dwordx4 v[192:195], v[172:173], off
	global_load_dwordx4 v[214:217], v[172:173], off offset:16
	global_load_dwordx4 v[218:221], v[172:173], off offset:512
	global_load_dwordx4 v[222:225], v[172:173], off offset:528
	v_add_u32_e32 v160, 32, v162
	v_ashrrev_i32_e32 v161, 31, v160
	v_lshlrev_b64 v[160:161], 12, v[160:161]
	v_lshl_add_u64 v[168:169], s[20:21], 0, v[160:161]
	v_lshl_add_u64 v[168:169], v[168:169], 0, v[152:153]
	s_waitcnt vmcnt(19)
	v_pk_fma_f32 v[94:95], v[94:95], v[156:157], v[226:227]
	v_pk_fma_f32 v[96:97], v[96:97], v[154:155], v[228:229]
	global_store_dwordx4 v[168:169], v[94:97], off
	s_waitcnt vmcnt(19)
	v_pk_fma_f32 v[88:89], v[88:89], v[148:149], v[230:231]
	v_pk_fma_f32 v[90:91], v[90:91], v[150:151], v[232:233]
	global_store_dwordx4 v[168:169], v[88:91], off offset:16
	s_waitcnt vmcnt(19)
	v_pk_fma_f32 v[84:85], v[84:85], v[144:145], v[234:235]
	v_pk_fma_f32 v[86:87], v[86:87], v[146:147], v[236:237]
	global_store_dwordx4 v[168:169], v[84:87], off offset:512
	s_waitcnt vmcnt(19)
	v_pk_fma_f32 v[80:81], v[80:81], v[140:141], v[238:239]
	v_pk_fma_f32 v[82:83], v[82:83], v[142:143], v[240:241]
	global_store_dwordx4 v[168:169], v[80:83], off offset:528
	v_add_u32_e32 v160, 144, v162
	v_ashrrev_i32_e32 v161, 31, v160
	v_lshlrev_b64 v[160:161], 12, v[160:161]
	v_lshl_add_u64 v[174:175], s[2:3], 0, v[160:161]
	v_lshl_add_u64 v[174:175], v[174:175], 0, v[152:153]
	global_load_dwordx4 v[226:229], v[174:175], off
	global_load_dwordx4 v[230:233], v[174:175], off offset:16
	global_load_dwordx4 v[234:237], v[174:175], off offset:512
	global_load_dwordx4 v[238:241], v[174:175], off offset:528
	v_add_u32_e32 v160, 48, v162
	v_ashrrev_i32_e32 v161, 31, v160
	v_lshlrev_b64 v[160:161], 12, v[160:161]
	v_lshl_add_u64 v[168:169], s[20:21], 0, v[160:161]
	v_lshl_add_u64 v[168:169], v[168:169], 0, v[152:153]
	s_waitcnt vmcnt(19)
	v_pk_fma_f32 v[76:77], v[76:77], v[156:157], v[176:177]
	v_pk_fma_f32 v[78:79], v[78:79], v[154:155], v[178:179]
	global_store_dwordx4 v[168:169], v[76:79], off
	s_waitcnt vmcnt(19)
	v_pk_fma_f32 v[72:73], v[72:73], v[148:149], v[180:181]
	v_pk_fma_f32 v[74:75], v[74:75], v[150:151], v[182:183]
	global_store_dwordx4 v[168:169], v[72:75], off offset:16
	s_waitcnt vmcnt(19)
	v_pk_fma_f32 v[68:69], v[68:69], v[144:145], v[184:185]
	v_pk_fma_f32 v[70:71], v[70:71], v[146:147], v[186:187]
	global_store_dwordx4 v[168:169], v[68:71], off offset:512
	s_waitcnt vmcnt(19)
	v_pk_fma_f32 v[64:65], v[64:65], v[140:141], v[188:189]
	v_pk_fma_f32 v[66:67], v[66:67], v[142:143], v[190:191]
	global_store_dwordx4 v[168:169], v[64:67], off offset:528
	v_add_u32_e32 v160, 160, v162
	v_ashrrev_i32_e32 v161, 31, v160
	v_lshlrev_b64 v[160:161], 12, v[160:161]
	v_lshl_add_u64 v[170:171], s[2:3], 0, v[160:161]
	v_lshl_add_u64 v[170:171], v[170:171], 0, v[152:153]
	global_load_dwordx4 v[176:179], v[170:171], off
	global_load_dwordx4 v[180:183], v[170:171], off offset:16
	global_load_dwordx4 v[184:187], v[170:171], off offset:512
	global_load_dwordx4 v[188:191], v[170:171], off offset:528
	v_add_u32_e32 v160, 128, v162
	v_ashrrev_i32_e32 v161, 31, v160
	v_lshlrev_b64 v[160:161], 12, v[160:161]
	v_lshl_add_u64 v[168:169], s[20:21], 0, v[160:161]
	v_lshl_add_u64 v[168:169], v[168:169], 0, v[152:153]
	s_waitcnt vmcnt(19)
	v_pk_fma_f32 v[60:61], v[60:61], v[156:157], v[192:193]
	v_pk_fma_f32 v[62:63], v[62:63], v[154:155], v[194:195]
	global_store_dwordx4 v[168:169], v[60:63], off
	s_waitcnt vmcnt(19)
	v_pk_fma_f32 v[56:57], v[56:57], v[148:149], v[214:215]
	v_pk_fma_f32 v[58:59], v[58:59], v[150:151], v[216:217]
	global_store_dwordx4 v[168:169], v[56:59], off offset:16
	s_waitcnt vmcnt(19)
	v_pk_fma_f32 v[52:53], v[52:53], v[144:145], v[218:219]
	v_pk_fma_f32 v[54:55], v[54:55], v[146:147], v[220:221]
	global_store_dwordx4 v[168:169], v[52:55], off offset:512
	s_waitcnt vmcnt(19)
	v_pk_fma_f32 v[48:49], v[48:49], v[140:141], v[222:223]
	v_pk_fma_f32 v[50:51], v[50:51], v[142:143], v[224:225]
	global_store_dwordx4 v[168:169], v[48:51], off offset:528
	v_add_u32_e32 v160, 176, v162
	v_ashrrev_i32_e32 v161, 31, v160
	v_lshlrev_b64 v[160:161], 12, v[160:161]
	v_lshl_add_u64 v[172:173], s[2:3], 0, v[160:161]
	v_lshl_add_u64 v[172:173], v[172:173], 0, v[152:153]
	global_load_dwordx4 v[192:195], v[172:173], off
	global_load_dwordx4 v[214:217], v[172:173], off offset:16
	global_load_dwordx4 v[218:221], v[172:173], off offset:512
	global_load_dwordx4 v[222:225], v[172:173], off offset:528
	v_add_u32_e32 v160, 144, v162
	v_ashrrev_i32_e32 v161, 31, v160
	v_lshlrev_b64 v[160:161], 12, v[160:161]
	v_lshl_add_u64 v[168:169], s[20:21], 0, v[160:161]
	v_lshl_add_u64 v[168:169], v[168:169], 0, v[152:153]
	s_waitcnt vmcnt(19)
	v_pk_fma_f32 v[44:45], v[44:45], v[156:157], v[226:227]
	v_pk_fma_f32 v[46:47], v[46:47], v[154:155], v[228:229]
	global_store_dwordx4 v[168:169], v[44:47], off
	s_waitcnt vmcnt(19)
	v_pk_fma_f32 v[40:41], v[40:41], v[148:149], v[230:231]
	v_pk_fma_f32 v[42:43], v[42:43], v[150:151], v[232:233]
	global_store_dwordx4 v[168:169], v[40:43], off offset:16
	s_waitcnt vmcnt(19)
	v_pk_fma_f32 v[36:37], v[36:37], v[144:145], v[234:235]
	v_pk_fma_f32 v[38:39], v[38:39], v[146:147], v[236:237]
	global_store_dwordx4 v[168:169], v[36:39], off offset:512
	s_waitcnt vmcnt(19)
	v_pk_fma_f32 v[32:33], v[32:33], v[140:141], v[238:239]
	v_pk_fma_f32 v[34:35], v[34:35], v[142:143], v[240:241]
	global_store_dwordx4 v[168:169], v[32:35], off offset:528
	v_add_u32_e32 v160, 160, v162
	v_ashrrev_i32_e32 v161, 31, v160
	v_lshlrev_b64 v[160:161], 12, v[160:161]
	v_lshl_add_u64 v[168:169], s[20:21], 0, v[160:161]
	v_lshl_add_u64 v[168:169], v[168:169], 0, v[152:153]
	s_waitcnt vmcnt(15)
	v_pk_fma_f32 v[28:29], v[28:29], v[156:157], v[176:177]
	v_pk_fma_f32 v[30:31], v[30:31], v[154:155], v[178:179]
	global_store_dwordx4 v[168:169], v[28:31], off
	s_waitcnt vmcnt(15)
	v_pk_fma_f32 v[24:25], v[24:25], v[148:149], v[180:181]
	v_pk_fma_f32 v[26:27], v[26:27], v[150:151], v[182:183]
	global_store_dwordx4 v[168:169], v[24:27], off offset:16
	s_waitcnt vmcnt(15)
	v_pk_fma_f32 v[20:21], v[20:21], v[144:145], v[184:185]
	v_pk_fma_f32 v[22:23], v[22:23], v[146:147], v[186:187]
	global_store_dwordx4 v[168:169], v[20:23], off offset:512
	s_waitcnt vmcnt(15)
	v_pk_fma_f32 v[16:17], v[16:17], v[140:141], v[188:189]
	v_pk_fma_f32 v[18:19], v[18:19], v[142:143], v[190:191]
	global_store_dwordx4 v[168:169], v[16:19], off offset:528
	v_add_u32_e32 v160, 176, v162
	v_ashrrev_i32_e32 v161, 31, v160
	v_lshlrev_b64 v[160:161], 12, v[160:161]
	v_lshl_add_u64 v[168:169], s[20:21], 0, v[160:161]
	v_lshl_add_u64 v[168:169], v[168:169], 0, v[152:153]
	s_waitcnt vmcnt(11)
	v_pk_fma_f32 v[12:13], v[12:13], v[156:157], v[192:193]
	v_pk_fma_f32 v[14:15], v[14:15], v[154:155], v[194:195]
	global_store_dwordx4 v[168:169], v[12:15], off
	s_waitcnt vmcnt(11)
	v_pk_fma_f32 v[8:9], v[8:9], v[148:149], v[214:215]
	v_pk_fma_f32 v[10:11], v[10:11], v[150:151], v[216:217]
	global_store_dwordx4 v[168:169], v[8:11], off offset:16
	s_waitcnt vmcnt(11)
	v_pk_fma_f32 v[4:5], v[4:5], v[144:145], v[218:219]
	v_pk_fma_f32 v[6:7], v[6:7], v[146:147], v[220:221]
	global_store_dwordx4 v[168:169], v[4:7], off offset:512
	s_waitcnt vmcnt(11)
	v_pk_fma_f32 v[0:1], v[0:1], v[140:141], v[222:223]
	v_pk_fma_f32 v[2:3], v[2:3], v[142:143], v[224:225]
	global_store_dwordx4 v[168:169], v[0:3], off offset:528
	s_mov_b64 s[28:29], -1
	s_cbranch_vccnz .LBB0_583
	s_andn2_b64 vcc, exec, s[18:19]
	s_cbranch_vccnz .LBB0_582
	s_barrier
	s_branch .LBB0_582

.LBB0_1522:
	s_ashr_i32 s28, s59, 3
	v_lshl_add_u32 v162, s59, 8, v159
	v_lshl_or_b32 v130, s60, 8, v165
	s_mul_hi_i32 s29, s28, 0x9000
	s_mul_i32 s28, s28, 0x9000
	v_ashrrev_i32_e32 v163, 31, v162
	s_add_u32 s28, s50, s28
	v_ashrrev_i32_e32 v131, 31, v130
	s_addc_u32 s29, s51, s29
	v_lshlrev_b64 v[156:157], 2, v[130:131]
	v_lshl_add_u64 v[134:135], s[28:29], 0, v[156:157]
	global_load_dwordx4 v[138:141], v[134:135], off offset:16
	global_load_dwordx4 v[142:145], v[134:135], off
	global_load_dwordx4 v[130:133], v[134:135], off offset:528
	s_nop 0
	global_load_dwordx4 v[134:137], v[134:135], off offset:512
	v_mov_b32_e32 v160, v162
	v_ashrrev_i32_e32 v161, 31, v160
	v_lshlrev_b64 v[160:161], 12, v[160:161]
	v_lshl_add_u64 v[170:171], s[18:19], 0, v[160:161]
	v_lshl_add_u64 v[170:171], v[170:171], 0, v[156:157]
	global_load_dwordx4 v[176:179], v[170:171], off
	global_load_dwordx4 v[180:183], v[170:171], off offset:16
	global_load_dwordx4 v[184:187], v[170:171], off offset:512
	global_load_dwordx4 v[188:191], v[170:171], off offset:528
	v_add_u32_e32 v160, 16, v162
	v_ashrrev_i32_e32 v161, 31, v160
	v_lshlrev_b64 v[160:161], 12, v[160:161]
	v_lshl_add_u64 v[172:173], s[18:19], 0, v[160:161]
	v_lshl_add_u64 v[172:173], v[172:173], 0, v[156:157]
	global_load_dwordx4 v[192:195], v[172:173], off
	global_load_dwordx4 v[214:217], v[172:173], off offset:16
	global_load_dwordx4 v[218:221], v[172:173], off offset:512
	global_load_dwordx4 v[222:225], v[172:173], off offset:528
	v_add_u32_e32 v160, 32, v162
	v_ashrrev_i32_e32 v161, 31, v160
	v_lshlrev_b64 v[160:161], 12, v[160:161]
	v_lshl_add_u64 v[174:175], s[18:19], 0, v[160:161]
	v_lshl_add_u64 v[174:175], v[174:175], 0, v[156:157]
	global_load_dwordx4 v[226:229], v[174:175], off
	global_load_dwordx4 v[230:233], v[174:175], off offset:16
	global_load_dwordx4 v[234:237], v[174:175], off offset:512
	global_load_dwordx4 v[238:241], v[174:175], off offset:528
	s_mov_b64 s[28:29], 0x80000
	s_and_b64 vcc, exec, s[4:5]
	s_waitcnt vmcnt(12)
	v_mov_b32_e32 v160, v162
	v_ashrrev_i32_e32 v161, 31, v160
	v_lshlrev_b64 v[160:161], 12, v[160:161]
	v_lshl_add_u64 v[168:169], s[20:21], 0, v[160:161]
	v_lshl_add_u64 v[168:169], v[168:169], 0, v[156:157]
	s_waitcnt vmcnt(11)
	v_pk_fma_f32 v[126:127], v[126:127], v[142:143], v[176:177]
	v_pk_fma_f32 v[128:129], v[128:129], v[144:145], v[178:179]
	global_store_dwordx4 v[168:169], v[126:129], off
	s_waitcnt vmcnt(11)
	v_pk_fma_f32 v[122:123], v[122:123], v[138:139], v[180:181]
	v_pk_fma_f32 v[124:125], v[124:125], v[140:141], v[182:183]
	global_store_dwordx4 v[168:169], v[122:125], off offset:16
	s_waitcnt vmcnt(11)
	v_pk_fma_f32 v[118:119], v[118:119], v[134:135], v[184:185]
	v_pk_fma_f32 v[120:121], v[120:121], v[136:137], v[186:187]
	global_store_dwordx4 v[168:169], v[118:121], off offset:512
	s_waitcnt vmcnt(11)
	v_pk_fma_f32 v[114:115], v[114:115], v[130:131], v[188:189]
	v_pk_fma_f32 v[116:117], v[116:117], v[132:133], v[190:191]
	global_store_dwordx4 v[168:169], v[114:117], off offset:528
	v_add_u32_e32 v160, 48, v162
	v_ashrrev_i32_e32 v161, 31, v160
	v_lshlrev_b64 v[160:161], 12, v[160:161]
	v_lshl_add_u64 v[170:171], s[18:19], 0, v[160:161]
	v_lshl_add_u64 v[170:171], v[170:171], 0, v[156:157]
	global_load_dwordx4 v[176:179], v[170:171], off
	global_load_dwordx4 v[180:183], v[170:171], off offset:16
	global_load_dwordx4 v[184:187], v[170:171], off offset:512
	global_load_dwordx4 v[188:191], v[170:171], off offset:528
	v_add_u32_e32 v160, 16, v162
	v_ashrrev_i32_e32 v161, 31, v160
	v_lshlrev_b64 v[160:161], 12, v[160:161]
	v_lshl_add_u64 v[168:169], s[20:21], 0, v[160:161]
	v_lshl_add_u64 v[168:169], v[168:169], 0, v[156:157]
	s_waitcnt vmcnt(15)
	v_pk_fma_f32 v[110:111], v[110:111], v[142:143], v[192:193]
	v_pk_fma_f32 v[112:113], v[112:113], v[144:145], v[194:195]
	global_store_dwordx4 v[168:169], v[110:113], off
	s_waitcnt vmcnt(15)
	v_pk_fma_f32 v[106:107], v[106:107], v[138:139], v[214:215]
	v_pk_fma_f32 v[108:109], v[108:109], v[140:141], v[216:217]
	global_store_dwordx4 v[168:169], v[106:109], off offset:16
	s_waitcnt vmcnt(15)
	v_pk_fma_f32 v[102:103], v[102:103], v[134:135], v[218:219]
	v_pk_fma_f32 v[104:105], v[104:105], v[136:137], v[220:221]
	global_store_dwordx4 v[168:169], v[102:105], off offset:512
	s_waitcnt vmcnt(15)
	v_pk_fma_f32 v[98:99], v[98:99], v[130:131], v[222:223]
	v_pk_fma_f32 v[100:101], v[100:101], v[132:133], v[224:225]
	global_store_dwordx4 v[168:169], v[98:101], off offset:528
	v_add_u32_e32 v160, 128, v162
	v_ashrrev_i32_e32 v161, 31, v160
	v_lshlrev_b64 v[160:161], 12, v[160:161]
	v_lshl_add_u64 v[172:173], s[18:19], 0, v[160:161]
	v_lshl_add_u64 v[172:173], v[172:173], 0, v[156:157]
	global_load_dwordx4 v[192:195], v[172:173], off
	global_load_dwordx4 v[214:217], v[172:173], off offset:16
	global_load_dwordx4 v[218:221], v[172:173], off offset:512
	global_load_dwordx4 v[222:225], v[172:173], off offset:528
	v_add_u32_e32 v160, 32, v162
	v_ashrrev_i32_e32 v161, 31, v160
	v_lshlrev_b64 v[160:161], 12, v[160:161]
	v_lshl_add_u64 v[168:169], s[20:21], 0, v[160:161]
	v_lshl_add_u64 v[168:169], v[168:169], 0, v[156:157]
	s_waitcnt vmcnt(19)
	v_pk_fma_f32 v[94:95], v[94:95], v[142:143], v[226:227]
	v_pk_fma_f32 v[96:97], v[96:97], v[144:145], v[228:229]
	global_store_dwordx4 v[168:169], v[94:97], off
	s_waitcnt vmcnt(19)
	v_pk_fma_f32 v[88:89], v[88:89], v[138:139], v[230:231]
	v_pk_fma_f32 v[90:91], v[90:91], v[140:141], v[232:233]
	global_store_dwordx4 v[168:169], v[88:91], off offset:16
	s_waitcnt vmcnt(19)
	v_pk_fma_f32 v[84:85], v[84:85], v[134:135], v[234:235]
	v_pk_fma_f32 v[86:87], v[86:87], v[136:137], v[236:237]
	global_store_dwordx4 v[168:169], v[84:87], off offset:512
	s_waitcnt vmcnt(19)
	v_pk_fma_f32 v[80:81], v[80:81], v[130:131], v[238:239]
	v_pk_fma_f32 v[82:83], v[82:83], v[132:133], v[240:241]
	global_store_dwordx4 v[168:169], v[80:83], off offset:528
	v_add_u32_e32 v160, 144, v162
	v_ashrrev_i32_e32 v161, 31, v160
	v_lshlrev_b64 v[160:161], 12, v[160:161]
	v_lshl_add_u64 v[174:175], s[18:19], 0, v[160:161]
	v_lshl_add_u64 v[174:175], v[174:175], 0, v[156:157]
	global_load_dwordx4 v[226:229], v[174:175], off
	global_load_dwordx4 v[230:233], v[174:175], off offset:16
	global_load_dwordx4 v[234:237], v[174:175], off offset:512
	global_load_dwordx4 v[238:241], v[174:175], off offset:528
	v_add_u32_e32 v160, 48, v162
	v_ashrrev_i32_e32 v161, 31, v160
	v_lshlrev_b64 v[160:161], 12, v[160:161]
	v_lshl_add_u64 v[168:169], s[20:21], 0, v[160:161]
	v_lshl_add_u64 v[168:169], v[168:169], 0, v[156:157]
	s_waitcnt vmcnt(19)
	v_pk_fma_f32 v[76:77], v[76:77], v[142:143], v[176:177]
	v_pk_fma_f32 v[78:79], v[78:79], v[144:145], v[178:179]
	global_store_dwordx4 v[168:169], v[76:79], off
	s_waitcnt vmcnt(19)
	v_pk_fma_f32 v[72:73], v[72:73], v[138:139], v[180:181]
	v_pk_fma_f32 v[74:75], v[74:75], v[140:141], v[182:183]
	global_store_dwordx4 v[168:169], v[72:75], off offset:16
	s_waitcnt vmcnt(19)
	v_pk_fma_f32 v[68:69], v[68:69], v[134:135], v[184:185]
	v_pk_fma_f32 v[70:71], v[70:71], v[136:137], v[186:187]
	global_store_dwordx4 v[168:169], v[68:71], off offset:512
	s_waitcnt vmcnt(19)
	v_pk_fma_f32 v[64:65], v[64:65], v[130:131], v[188:189]
	v_pk_fma_f32 v[66:67], v[66:67], v[132:133], v[190:191]
	global_store_dwordx4 v[168:169], v[64:67], off offset:528
	v_add_u32_e32 v160, 160, v162
	v_ashrrev_i32_e32 v161, 31, v160
	v_lshlrev_b64 v[160:161], 12, v[160:161]
	v_lshl_add_u64 v[170:171], s[18:19], 0, v[160:161]
	v_lshl_add_u64 v[170:171], v[170:171], 0, v[156:157]
	global_load_dwordx4 v[176:179], v[170:171], off
	global_load_dwordx4 v[180:183], v[170:171], off offset:16
	global_load_dwordx4 v[184:187], v[170:171], off offset:512
	global_load_dwordx4 v[188:191], v[170:171], off offset:528
	v_add_u32_e32 v160, 128, v162
	v_ashrrev_i32_e32 v161, 31, v160
	v_lshlrev_b64 v[160:161], 12, v[160:161]
	v_lshl_add_u64 v[168:169], s[20:21], 0, v[160:161]
	v_lshl_add_u64 v[168:169], v[168:169], 0, v[156:157]
	s_waitcnt vmcnt(19)
	v_pk_fma_f32 v[60:61], v[60:61], v[142:143], v[192:193]
	v_pk_fma_f32 v[62:63], v[62:63], v[144:145], v[194:195]
	global_store_dwordx4 v[168:169], v[60:63], off
	s_waitcnt vmcnt(19)
	v_pk_fma_f32 v[56:57], v[56:57], v[138:139], v[214:215]
	v_pk_fma_f32 v[58:59], v[58:59], v[140:141], v[216:217]
	global_store_dwordx4 v[168:169], v[56:59], off offset:16
	s_waitcnt vmcnt(19)
	v_pk_fma_f32 v[52:53], v[52:53], v[134:135], v[218:219]
	v_pk_fma_f32 v[54:55], v[54:55], v[136:137], v[220:221]
	global_store_dwordx4 v[168:169], v[52:55], off offset:512
	s_waitcnt vmcnt(19)
	v_pk_fma_f32 v[48:49], v[48:49], v[130:131], v[222:223]
	v_pk_fma_f32 v[50:51], v[50:51], v[132:133], v[224:225]
	global_store_dwordx4 v[168:169], v[48:51], off offset:528
	v_add_u32_e32 v160, 176, v162
	v_ashrrev_i32_e32 v161, 31, v160
	v_lshlrev_b64 v[160:161], 12, v[160:161]
	v_lshl_add_u64 v[172:173], s[18:19], 0, v[160:161]
	v_lshl_add_u64 v[172:173], v[172:173], 0, v[156:157]
	global_load_dwordx4 v[192:195], v[172:173], off
	global_load_dwordx4 v[214:217], v[172:173], off offset:16
	global_load_dwordx4 v[218:221], v[172:173], off offset:512
	global_load_dwordx4 v[222:225], v[172:173], off offset:528
	v_add_u32_e32 v160, 144, v162
	v_ashrrev_i32_e32 v161, 31, v160
	v_lshlrev_b64 v[160:161], 12, v[160:161]
	v_lshl_add_u64 v[168:169], s[20:21], 0, v[160:161]
	v_lshl_add_u64 v[168:169], v[168:169], 0, v[156:157]
	s_waitcnt vmcnt(19)
	v_pk_fma_f32 v[44:45], v[44:45], v[142:143], v[226:227]
	v_pk_fma_f32 v[46:47], v[46:47], v[144:145], v[228:229]
	global_store_dwordx4 v[168:169], v[44:47], off
	s_waitcnt vmcnt(19)
	v_pk_fma_f32 v[40:41], v[40:41], v[138:139], v[230:231]
	v_pk_fma_f32 v[42:43], v[42:43], v[140:141], v[232:233]
	global_store_dwordx4 v[168:169], v[40:43], off offset:16
	s_waitcnt vmcnt(19)
	v_pk_fma_f32 v[36:37], v[36:37], v[134:135], v[234:235]
	v_pk_fma_f32 v[38:39], v[38:39], v[136:137], v[236:237]
	global_store_dwordx4 v[168:169], v[36:39], off offset:512
	s_waitcnt vmcnt(19)
	v_pk_fma_f32 v[32:33], v[32:33], v[130:131], v[238:239]
	v_pk_fma_f32 v[34:35], v[34:35], v[132:133], v[240:241]
	global_store_dwordx4 v[168:169], v[32:35], off offset:528
	v_add_u32_e32 v160, 160, v162
	v_ashrrev_i32_e32 v161, 31, v160
	v_lshlrev_b64 v[160:161], 12, v[160:161]
	v_lshl_add_u64 v[168:169], s[20:21], 0, v[160:161]
	v_lshl_add_u64 v[168:169], v[168:169], 0, v[156:157]
	s_waitcnt vmcnt(15)
	v_pk_fma_f32 v[28:29], v[28:29], v[142:143], v[176:177]
	v_pk_fma_f32 v[30:31], v[30:31], v[144:145], v[178:179]
	global_store_dwordx4 v[168:169], v[28:31], off
	s_waitcnt vmcnt(15)
	v_pk_fma_f32 v[24:25], v[24:25], v[138:139], v[180:181]
	v_pk_fma_f32 v[26:27], v[26:27], v[140:141], v[182:183]
	global_store_dwordx4 v[168:169], v[24:27], off offset:16
	s_waitcnt vmcnt(15)
	v_pk_fma_f32 v[20:21], v[20:21], v[134:135], v[184:185]
	v_pk_fma_f32 v[22:23], v[22:23], v[136:137], v[186:187]
	global_store_dwordx4 v[168:169], v[20:23], off offset:512
	s_waitcnt vmcnt(15)
	v_pk_fma_f32 v[16:17], v[16:17], v[130:131], v[188:189]
	v_pk_fma_f32 v[18:19], v[18:19], v[132:133], v[190:191]
	global_store_dwordx4 v[168:169], v[16:19], off offset:528
	v_add_u32_e32 v160, 176, v162
	v_ashrrev_i32_e32 v161, 31, v160
	v_lshlrev_b64 v[160:161], 12, v[160:161]
	v_lshl_add_u64 v[168:169], s[20:21], 0, v[160:161]
	v_lshl_add_u64 v[168:169], v[168:169], 0, v[156:157]
	s_waitcnt vmcnt(11)
	v_pk_fma_f32 v[12:13], v[12:13], v[142:143], v[192:193]
	v_pk_fma_f32 v[14:15], v[14:15], v[144:145], v[194:195]
	global_store_dwordx4 v[168:169], v[12:15], off
	s_waitcnt vmcnt(11)
	v_pk_fma_f32 v[8:9], v[8:9], v[138:139], v[214:215]
	v_pk_fma_f32 v[10:11], v[10:11], v[140:141], v[216:217]
	global_store_dwordx4 v[168:169], v[8:11], off offset:16
	s_waitcnt vmcnt(11)
	v_pk_fma_f32 v[4:5], v[4:5], v[134:135], v[218:219]
	v_pk_fma_f32 v[6:7], v[6:7], v[136:137], v[220:221]
	global_store_dwordx4 v[168:169], v[4:7], off offset:512
	s_waitcnt vmcnt(11)
	v_pk_fma_f32 v[0:1], v[0:1], v[130:131], v[222:223]
	v_pk_fma_f32 v[2:3], v[2:3], v[132:133], v[224:225]
	global_store_dwordx4 v[168:169], v[0:3], off offset:528
	s_mov_b64 s[28:29], -1
	s_cbranch_vccnz .LBB0_1505
	s_andn2_b64 vcc, exec, s[16:17]
	s_cbranch_vccnz .LBB0_1504
	s_barrier
	s_branch .LBB0_1504
